# P0: LAM loop unrolled with 4-deep load window, conv_plain calls spread over idle waves (guarded NGW==2048); S5 scan: redundant lgkmcnt(0) dropped
# baseline (speedup 1.0000x reference)
.LBB0_69:
	s_load_dwordx16 s[8:23], s[0:1], 0x40
	s_add_u32 s4, s82, 0x1f100000
	s_waitcnt lgkmcnt(0)
	v_writelane_b32 v252, s8, 27
	s_nop 1
	v_writelane_b32 v252, s9, 28
	v_writelane_b32 v252, s10, 29
	v_writelane_b32 v252, s11, 30
	v_writelane_b32 v252, s12, 31
	v_writelane_b32 v252, s13, 32
	v_writelane_b32 v252, s14, 33
	v_writelane_b32 v252, s15, 34
	v_writelane_b32 v252, s16, 35
	v_writelane_b32 v252, s17, 36
	v_writelane_b32 v252, s18, 37
	v_writelane_b32 v252, s19, 38
	v_writelane_b32 v252, s20, 39
	v_writelane_b32 v252, s21, 40
	v_writelane_b32 v252, s22, 41
	v_writelane_b32 v252, s23, 42
	v_writelane_b32 v252, s4, 43
	s_addc_u32 s4, s83, 0
	v_writelane_b32 v252, s4, 44
	s_cmpk_lg_i32 s89, 0x800
	s_cbranch_scc1 .Lcp_orig
	s_cmpk_lt_i32 s68, 0x700
	s_cbranch_scc1 .LBB0_78
	s_add_i32 s98, s68, 0xfffff880
	s_cmpk_ge_i32 s68, 0x780
	s_cbranch_scc1 .Lcp2_only
	v_mov_b32_e32 v1, 0
	s_movk_i32 s10, 0x84
	s_add_i32 s11, s68, 0xfffff900
	s_branch .LBB0_71
.Lcp_orig:
	s_cmpk_gt_i32 s68, 0x7f
	s_cbranch_scc1 .LBB0_78
	v_mov_b32_e32 v1, 0
	s_movk_i32 s10, 0x84
	s_mov_b32 s11, s68

.LBB0_72:
	s_lshl_b32 s13, s9, 1
	s_lshl_b32 s14, s12, 1
	v_add_u32_e32 v38, s13, v6
	v_add_u32_e32 v40, s14, v7
	v_add_u32_e32 v42, s13, v10
	v_add_u32_e32 v44, s14, v11
	v_add_u32_e32 v46, s13, v14
	v_add_u32_e32 v48, s14, v15
	v_add_u32_e32 v50, s13, v18
	v_add_u32_e32 v52, s14, v19
	v_add_u32_e32 v54, s13, v22
	v_add_u32_e32 v56, s14, v23
	v_add_u32_e32 v58, s13, v26
	v_add_u32_e32 v60, s14, v27
	v_add_u32_e32 v62, s13, v30
	v_add_u32_e32 v64, s14, v31
	v_add_u32_e32 v66, s13, v34
	v_add_u32_e32 v68, s14, v35
	v_ashrrev_i32_e32 v39, 31, v38
	v_ashrrev_i32_e32 v41, 31, v40
	v_ashrrev_i32_e32 v43, 31, v42
	v_ashrrev_i32_e32 v45, 31, v44
	v_ashrrev_i32_e32 v47, 31, v46
	v_ashrrev_i32_e32 v49, 31, v48
	v_ashrrev_i32_e32 v51, 31, v50
	v_ashrrev_i32_e32 v53, 31, v52
	v_ashrrev_i32_e32 v55, 31, v54
	v_ashrrev_i32_e32 v57, 31, v56
	v_ashrrev_i32_e32 v59, 31, v58
	v_ashrrev_i32_e32 v61, 31, v60
	v_ashrrev_i32_e32 v63, 31, v62
	v_ashrrev_i32_e32 v65, 31, v64
	v_ashrrev_i32_e32 v67, 31, v66
	v_ashrrev_i32_e32 v69, 31, v68
	v_lshlrev_b64 v[38:39], 11, v[38:39]
	v_lshlrev_b64 v[40:41], 11, v[40:41]
	v_lshlrev_b64 v[42:43], 11, v[42:43]
	v_lshlrev_b64 v[44:45], 11, v[44:45]
	v_lshlrev_b64 v[46:47], 11, v[46:47]
	v_lshlrev_b64 v[48:49], 11, v[48:49]
	v_lshlrev_b64 v[50:51], 11, v[50:51]
	v_lshlrev_b64 v[52:53], 11, v[52:53]
	v_lshlrev_b64 v[54:55], 11, v[54:55]
	v_lshlrev_b64 v[56:57], 11, v[56:57]
	v_lshlrev_b64 v[58:59], 11, v[58:59]
	v_lshlrev_b64 v[60:61], 11, v[60:61]
	v_lshlrev_b64 v[62:63], 11, v[62:63]
	v_lshlrev_b64 v[64:65], 11, v[64:65]
	v_lshlrev_b64 v[66:67], 11, v[66:67]
	v_lshlrev_b64 v[68:69], 11, v[68:69]
	v_lshl_add_u64 v[38:39], v[2:3], 0, v[38:39]
	v_lshl_add_u64 v[40:41], v[2:3], 0, v[40:41]
	v_lshl_add_u64 v[42:43], v[2:3], 0, v[42:43]
	v_lshl_add_u64 v[44:45], v[2:3], 0, v[44:45]
	v_lshl_add_u64 v[46:47], v[2:3], 0, v[46:47]
	v_lshl_add_u64 v[48:49], v[2:3], 0, v[48:49]
	v_lshl_add_u64 v[50:51], v[2:3], 0, v[50:51]
	v_lshl_add_u64 v[52:53], v[2:3], 0, v[52:53]
	v_lshl_add_u64 v[54:55], v[2:3], 0, v[54:55]
	v_lshl_add_u64 v[56:57], v[2:3], 0, v[56:57]
	v_lshl_add_u64 v[58:59], v[2:3], 0, v[58:59]
	v_lshl_add_u64 v[60:61], v[2:3], 0, v[60:61]
	v_lshl_add_u64 v[62:63], v[2:3], 0, v[62:63]
	v_lshl_add_u64 v[64:65], v[2:3], 0, v[64:65]
	v_lshl_add_u64 v[66:67], v[2:3], 0, v[66:67]
	v_lshl_add_u64 v[68:69], v[2:3], 0, v[68:69]
	global_load_dword v37, v[38:39], off
	global_load_dword v70, v[40:41], off
	global_load_dword v71, v[42:43], off
	global_load_dword v72, v[44:45], off
	global_load_dword v73, v[46:47], off
	global_load_dword v74, v[48:49], off
	global_load_dword v75, v[50:51], off
	global_load_dword v76, v[52:53], off
	global_load_dword v77, v[54:55], off
	global_load_dword v78, v[56:57], off
	global_load_dword v79, v[58:59], off
	global_load_dword v80, v[60:61], off
	global_load_dword v81, v[62:63], off
	global_load_dword v82, v[64:65], off
	global_load_dword v83, v[66:67], off
	global_load_dword v84, v[68:69], off
	s_add_i32 s9, s9, 16
	s_add_i32 s12, s12, 16
	s_add_i32 s5, s5, -16
	v_add_u32_e32 v38, s13, v4
	v_add_u32_e32 v40, s14, v5
	v_add_u32_e32 v42, s13, v8
	v_add_u32_e32 v44, s14, v9
	v_add_u32_e32 v46, s13, v12
	v_add_u32_e32 v48, s14, v13
	v_add_u32_e32 v50, s13, v16
	v_add_u32_e32 v52, s14, v17
	v_add_u32_e32 v54, s13, v20
	v_add_u32_e32 v56, s14, v21
	v_add_u32_e32 v58, s13, v24
	v_add_u32_e32 v60, s14, v25
	v_add_u32_e32 v62, s13, v28
	v_add_u32_e32 v64, s14, v29
	v_add_u32_e32 v66, s13, v32
	v_add_u32_e32 v68, s14, v33
	s_cmp_lg_u32 s5, 0
	v_mad_u64_u32 v[38:39], s[14:15], v38, s10, v[0:1]
	v_mad_u64_u32 v[40:41], s[14:15], v40, s10, v[0:1]
	v_mad_u64_u32 v[42:43], s[14:15], v42, s10, v[0:1]
	v_mad_u64_u32 v[44:45], s[14:15], v44, s10, v[0:1]
	v_mad_u64_u32 v[46:47], s[14:15], v46, s10, v[0:1]
	v_mad_u64_u32 v[48:49], s[14:15], v48, s10, v[0:1]
	v_mad_u64_u32 v[50:51], s[14:15], v50, s10, v[0:1]
	v_mad_u64_u32 v[52:53], s[14:15], v52, s10, v[0:1]
	v_mad_u64_u32 v[54:55], s[14:15], v54, s10, v[0:1]
	v_mad_u64_u32 v[56:57], s[14:15], v56, s10, v[0:1]
	v_mad_u64_u32 v[58:59], s[14:15], v58, s10, v[0:1]
	v_mad_u64_u32 v[60:61], s[14:15], v60, s10, v[0:1]
	v_mad_u64_u32 v[62:63], s[14:15], v62, s10, v[0:1]
	v_mad_u64_u32 v[64:65], s[14:15], v64, s10, v[0:1]
	v_mad_u64_u32 v[66:67], s[14:15], v66, s10, v[0:1]
	v_mad_u64_u32 v[68:69], s[14:15], v68, s10, v[0:1]
	s_waitcnt vmcnt(15)
	ds_write_b32 v38, v37
	s_waitcnt vmcnt(14)
	ds_write_b32 v40, v70
	s_waitcnt vmcnt(13)
	ds_write_b32 v42, v71
	s_waitcnt vmcnt(12)
	ds_write_b32 v44, v72
	s_waitcnt vmcnt(11)
	ds_write_b32 v46, v73
	s_waitcnt vmcnt(10)
	ds_write_b32 v48, v74
	s_waitcnt vmcnt(9)
	ds_write_b32 v50, v75
	s_waitcnt vmcnt(8)
	ds_write_b32 v52, v76
	s_waitcnt vmcnt(7)
	ds_write_b32 v54, v77
	s_waitcnt vmcnt(6)
	ds_write_b32 v56, v78
	s_waitcnt vmcnt(5)
	ds_write_b32 v58, v79
	s_waitcnt vmcnt(4)
	ds_write_b32 v60, v80
	s_waitcnt vmcnt(3)
	ds_write_b32 v62, v81
	s_waitcnt vmcnt(2)
	ds_write_b32 v64, v82
	s_waitcnt vmcnt(1)
	ds_write_b32 v66, v83
	s_waitcnt vmcnt(0)
	ds_write_b32 v68, v84
	s_cbranch_scc1 .LBB0_72
	v_lshlrev_b32_e32 v0, 3, v36
	v_ashrrev_i32_e32 v24, 3, v36
	v_and_b32_e32 v0, 56, v0
	v_mul_u32_u24_e32 v2, 0x84, v0
	v_lshlrev_b32_e32 v3, 2, v24
	s_waitcnt lgkmcnt(0)
	v_add3_u32 v28, s70, v2, v3
	s_ashr_i32 s9, s8, 31
	ds_read2_b32 v[6:7], v28 offset0:33 offset1:41
	ds_read2_b32 v[8:9], v28 offset1:8
	ds_read2_b32 v[10:11], v28 offset0:66 offset1:74
	ds_read2_b32 v[12:13], v28 offset0:99 offset1:107
	ds_read2_b32 v[14:15], v28 offset0:132 offset1:140
	ds_read2_b32 v[16:17], v28 offset0:165 offset1:173
	ds_read2_b32 v[18:19], v28 offset0:198 offset1:206
	ds_read2_b32 v[20:21], v28 offset0:231 offset1:239
	s_lshl_b64 s[8:9], s[8:9], 1
	v_readlane_b32 s5, v252, 43
	s_add_u32 s8, s5, s8
	v_readlane_b32 s5, v252, 44
	v_add_u32_e32 v24, s4, v24
	s_addc_u32 s9, s5, s9
	v_lshlrev_b32_e32 v0, 1, v0
	v_ashrrev_i32_e32 v25, 31, v24
	v_lshl_add_u64 v[22:23], s[8:9], 0, v[0:1]
	v_lshlrev_b64 v[26:27], 10, v[24:25]
	s_waitcnt lgkmcnt(6)
	v_cvt_pk_bf16_f32 v2, v8, v6
	s_waitcnt lgkmcnt(4)
	v_cvt_pk_bf16_f32 v3, v10, v12
	s_waitcnt lgkmcnt(2)
	v_cvt_pk_bf16_f32 v4, v14, v16
	s_waitcnt lgkmcnt(0)
	v_cvt_pk_bf16_f32 v5, v18, v20
	v_lshl_add_u64 v[26:27], v[22:23], 0, v[26:27]
	v_add_u32_e32 v6, 8, v24
	global_store_dwordx4 v[26:27], v[2:5], off
	s_add_i32 s11, s11, s89
	s_cmpk_lt_i32 s11, 0x80
	v_cvt_pk_bf16_f32 v2, v9, v7
	v_ashrrev_i32_e32 v7, 31, v6
	v_cvt_pk_bf16_f32 v3, v11, v13
	v_cvt_pk_bf16_f32 v4, v15, v17
	v_cvt_pk_bf16_f32 v5, v19, v21
	v_lshlrev_b64 v[6:7], 10, v[6:7]
	ds_read2_b32 v[8:9], v28 offset0:49 offset1:57
	ds_read2_b32 v[10:11], v28 offset0:16 offset1:24
	ds_read2_b32 v[12:13], v28 offset0:82 offset1:90
	ds_read2_b32 v[14:15], v28 offset0:115 offset1:123
	ds_read2_b32 v[16:17], v28 offset0:148 offset1:156
	ds_read2_b32 v[18:19], v28 offset0:181 offset1:189
	ds_read2_b32 v[20:21], v28 offset0:214 offset1:222
	ds_read2_b32 v[26:27], v28 offset0:247 offset1:255
	v_lshl_add_u64 v[6:7], v[22:23], 0, v[6:7]
	global_store_dwordx4 v[6:7], v[2:5], off
	v_add_u32_e32 v6, 16, v24
	v_ashrrev_i32_e32 v7, 31, v6
	v_lshlrev_b64 v[6:7], 10, v[6:7]
	s_waitcnt lgkmcnt(6)
	v_cvt_pk_bf16_f32 v2, v10, v8
	s_waitcnt lgkmcnt(4)
	v_cvt_pk_bf16_f32 v3, v12, v14
	s_waitcnt lgkmcnt(2)
	v_cvt_pk_bf16_f32 v4, v16, v18
	s_waitcnt lgkmcnt(0)
	v_cvt_pk_bf16_f32 v5, v20, v26
	v_lshl_add_u64 v[6:7], v[22:23], 0, v[6:7]
	global_store_dwordx4 v[6:7], v[2:5], off
	v_add_u32_e32 v6, 24, v24
	v_ashrrev_i32_e32 v7, 31, v6
	v_lshlrev_b64 v[6:7], 10, v[6:7]
	v_cvt_pk_bf16_f32 v2, v11, v9
	v_cvt_pk_bf16_f32 v3, v13, v15
	v_cvt_pk_bf16_f32 v4, v17, v19
	v_cvt_pk_bf16_f32 v5, v21, v27
	v_lshl_add_u64 v[6:7], v[22:23], 0, v[6:7]
	global_store_dwordx4 v[6:7], v[2:5], off
	s_waitcnt lgkmcnt(0)
	s_cbranch_scc1 .LBB0_71
	s_mov_b32 s98, s68
	s_cmpk_eq_i32 s89, 0x800
	s_cbranch_scc1 .LBB0_78
.Lcp2_only:
	s_load_dwordx16 s[8:23], s[0:1], 0x40
	v_mov_b32_e32 v1, 0
	s_waitcnt lgkmcnt(0)
	s_add_u32 s10, s14, 0x100000
	s_addc_u32 s11, s15, 0
	s_add_u32 s12, s82, 0x1f180000
	s_addc_u32 s13, s83, 0
	s_movk_i32 s14, 0x84
	s_mov_b32 s15, s98

.LBB0_118:
	v_lshl_add_u64 v[80:81], v[2:3], 0, s[4:5]
	v_lshl_add_u64 v[88:89], v[4:5], 0, s[4:5]
	v_lshl_add_u64 v[84:85], v[6:7], 0, s[4:5]
	v_lshl_add_u64 v[92:93], v[8:9], 0, s[4:5]
	global_load_dwordx4 v[64:67], v[80:81], off
	global_load_dwordx4 v[68:71], v[84:85], off
	global_load_dwordx4 v[72:75], v[88:89], off
	global_load_dwordx4 v[76:79], v[92:93], off
	s_nop 0
	global_load_dwordx4 v[80:83], v[80:81], off offset:16
	s_nop 0
	global_load_dwordx4 v[84:87], v[84:85], off offset:16
	s_nop 0
	global_load_dwordx4 v[88:91], v[88:89], off offset:16
	s_nop 0
	global_load_dwordx4 v[92:95], v[92:93], off offset:16
	s_add_u32 s4, s4, 32
	s_addc_u32 s5, s5, 0
	v_lshl_add_u64 v[112:113], v[2:3], 0, s[4:5]
	v_lshl_add_u64 v[120:121], v[4:5], 0, s[4:5]
	v_lshl_add_u64 v[116:117], v[6:7], 0, s[4:5]
	v_lshl_add_u64 v[124:125], v[8:9], 0, s[4:5]
	global_load_dwordx4 v[96:99], v[112:113], off
	global_load_dwordx4 v[100:103], v[116:117], off
	global_load_dwordx4 v[104:107], v[120:121], off
	global_load_dwordx4 v[108:111], v[124:125], off
	s_nop 0
	global_load_dwordx4 v[112:115], v[112:113], off offset:16
	s_nop 0
	global_load_dwordx4 v[116:119], v[116:117], off offset:16
	s_nop 0
	global_load_dwordx4 v[120:123], v[120:121], off offset:16
	s_nop 0
	global_load_dwordx4 v[124:127], v[124:125], off offset:16
	s_add_u32 s4, s4, 32
	s_addc_u32 s5, s5, 0
	v_lshl_add_u64 v[144:145], v[2:3], 0, s[4:5]
	v_lshl_add_u64 v[152:153], v[4:5], 0, s[4:5]
	v_lshl_add_u64 v[148:149], v[6:7], 0, s[4:5]
	v_lshl_add_u64 v[156:157], v[8:9], 0, s[4:5]
	global_load_dwordx4 v[128:131], v[144:145], off
	global_load_dwordx4 v[132:135], v[148:149], off
	global_load_dwordx4 v[136:139], v[152:153], off
	global_load_dwordx4 v[140:143], v[156:157], off
	s_nop 0
	global_load_dwordx4 v[144:147], v[144:145], off offset:16
	s_nop 0
	global_load_dwordx4 v[148:151], v[148:149], off offset:16
	s_nop 0
	global_load_dwordx4 v[152:155], v[152:153], off offset:16
	s_nop 0
	global_load_dwordx4 v[156:159], v[156:157], off offset:16
	s_add_u32 s4, s4, 32
	s_addc_u32 s5, s5, 0
	v_lshl_add_u64 v[176:177], v[2:3], 0, s[4:5]
	v_lshl_add_u64 v[184:185], v[4:5], 0, s[4:5]
	v_lshl_add_u64 v[180:181], v[6:7], 0, s[4:5]
	v_lshl_add_u64 v[188:189], v[8:9], 0, s[4:5]
	global_load_dwordx4 v[160:163], v[176:177], off
	global_load_dwordx4 v[164:167], v[180:181], off
	global_load_dwordx4 v[168:171], v[184:185], off
	global_load_dwordx4 v[172:175], v[188:189], off
	s_nop 0
	global_load_dwordx4 v[176:179], v[176:177], off offset:16
	s_nop 0
	global_load_dwordx4 v[180:183], v[180:181], off offset:16
	s_nop 0
	global_load_dwordx4 v[184:187], v[184:185], off offset:16
	s_nop 0
	global_load_dwordx4 v[188:191], v[188:189], off offset:16
	s_add_u32 s4, s4, 32
	s_addc_u32 s5, s5, 0
	s_waitcnt vmcnt(31)
	v_mov_b32_e32 v42, v64
	s_waitcnt vmcnt(30)
	v_mov_b32_e32 v43, v68
	s_waitcnt vmcnt(29)
	v_mov_b32_e32 v44, v72
	s_waitcnt vmcnt(28)
	v_mov_b32_e32 v45, v76
	v_mov_b32_e32 v68, v65
	v_mov_b32_e32 v76, v73
	v_pk_fma_f32 v[0:1], v[42:43], v[44:45], v[0:1]
	v_mov_b32_e32 v64, v66
	v_mov_b32_e32 v65, v70
	v_mov_b32_e32 v72, v74
	v_mov_b32_e32 v73, v78
	v_pk_fma_f32 v[0:1], v[68:69], v[76:77], v[0:1]
	v_mov_b32_e32 v70, v67
	v_mov_b32_e32 v78, v75
	v_pk_fma_f32 v[0:1], v[64:65], v[72:73], v[0:1]
	s_waitcnt vmcnt(27)
	v_mov_b32_e32 v66, v80
	s_waitcnt vmcnt(26)
	v_mov_b32_e32 v67, v84
	s_waitcnt vmcnt(25)
	v_mov_b32_e32 v74, v88
	s_waitcnt vmcnt(24)
	v_mov_b32_e32 v75, v92
	v_pk_fma_f32 v[0:1], v[70:71], v[78:79], v[0:1]
	v_mov_b32_e32 v84, v81
	v_mov_b32_e32 v92, v89
	v_pk_fma_f32 v[0:1], v[66:67], v[74:75], v[0:1]
	v_mov_b32_e32 v80, v82
	v_mov_b32_e32 v81, v86
	v_mov_b32_e32 v88, v90
	v_mov_b32_e32 v89, v94
	v_pk_fma_f32 v[0:1], v[84:85], v[92:93], v[0:1]
	v_mov_b32_e32 v86, v83
	v_mov_b32_e32 v94, v91
	v_pk_fma_f32 v[0:1], v[80:81], v[88:89], v[0:1]
	s_nop 0
	v_pk_fma_f32 v[0:1], v[86:87], v[94:95], v[0:1]
	v_lshl_add_u64 v[80:81], v[2:3], 0, s[4:5]
	v_lshl_add_u64 v[88:89], v[4:5], 0, s[4:5]
	v_lshl_add_u64 v[84:85], v[6:7], 0, s[4:5]
	v_lshl_add_u64 v[92:93], v[8:9], 0, s[4:5]
	global_load_dwordx4 v[64:67], v[80:81], off
	global_load_dwordx4 v[68:71], v[84:85], off
	global_load_dwordx4 v[72:75], v[88:89], off
	global_load_dwordx4 v[76:79], v[92:93], off
	s_nop 0
	global_load_dwordx4 v[80:83], v[80:81], off offset:16
	s_nop 0
	global_load_dwordx4 v[84:87], v[84:85], off offset:16
	s_nop 0
	global_load_dwordx4 v[88:91], v[88:89], off offset:16
	s_nop 0
	global_load_dwordx4 v[92:95], v[92:93], off offset:16
	s_add_u32 s4, s4, 32
	s_addc_u32 s5, s5, 0
	s_waitcnt vmcnt(31)
	v_mov_b32_e32 v42, v96
	s_waitcnt vmcnt(30)
	v_mov_b32_e32 v43, v100
	s_waitcnt vmcnt(29)
	v_mov_b32_e32 v44, v104
	s_waitcnt vmcnt(28)
	v_mov_b32_e32 v45, v108
	v_mov_b32_e32 v100, v97
	v_mov_b32_e32 v108, v105
	v_pk_fma_f32 v[0:1], v[42:43], v[44:45], v[0:1]
	v_mov_b32_e32 v96, v98
	v_mov_b32_e32 v97, v102
	v_mov_b32_e32 v104, v106
	v_mov_b32_e32 v105, v110
	v_pk_fma_f32 v[0:1], v[100:101], v[108:109], v[0:1]
	v_mov_b32_e32 v102, v99
	v_mov_b32_e32 v110, v107
	v_pk_fma_f32 v[0:1], v[96:97], v[104:105], v[0:1]
	s_waitcnt vmcnt(27)
	v_mov_b32_e32 v98, v112
	s_waitcnt vmcnt(26)
	v_mov_b32_e32 v99, v116
	s_waitcnt vmcnt(25)
	v_mov_b32_e32 v106, v120
	s_waitcnt vmcnt(24)
	v_mov_b32_e32 v107, v124
	v_pk_fma_f32 v[0:1], v[102:103], v[110:111], v[0:1]
	v_mov_b32_e32 v116, v113
	v_mov_b32_e32 v124, v121
	v_pk_fma_f32 v[0:1], v[98:99], v[106:107], v[0:1]
	v_mov_b32_e32 v112, v114
	v_mov_b32_e32 v113, v118
	v_mov_b32_e32 v120, v122
	v_mov_b32_e32 v121, v126
	v_pk_fma_f32 v[0:1], v[116:117], v[124:125], v[0:1]
	v_mov_b32_e32 v118, v115
	v_mov_b32_e32 v126, v123
	v_pk_fma_f32 v[0:1], v[112:113], v[120:121], v[0:1]
	s_nop 0
	v_pk_fma_f32 v[0:1], v[118:119], v[126:127], v[0:1]
	v_lshl_add_u64 v[112:113], v[2:3], 0, s[4:5]
	v_lshl_add_u64 v[120:121], v[4:5], 0, s[4:5]
	v_lshl_add_u64 v[116:117], v[6:7], 0, s[4:5]
	v_lshl_add_u64 v[124:125], v[8:9], 0, s[4:5]
	global_load_dwordx4 v[96:99], v[112:113], off
	global_load_dwordx4 v[100:103], v[116:117], off
	global_load_dwordx4 v[104:107], v[120:121], off
	global_load_dwordx4 v[108:111], v[124:125], off
	s_nop 0
	global_load_dwordx4 v[112:115], v[112:113], off offset:16
	s_nop 0
	global_load_dwordx4 v[116:119], v[116:117], off offset:16
	s_nop 0
	global_load_dwordx4 v[120:123], v[120:121], off offset:16
	s_nop 0
	global_load_dwordx4 v[124:127], v[124:125], off offset:16
	s_add_u32 s4, s4, 32
	s_addc_u32 s5, s5, 0
	s_waitcnt vmcnt(31)
	v_mov_b32_e32 v42, v128
	s_waitcnt vmcnt(30)
	v_mov_b32_e32 v43, v132
	s_waitcnt vmcnt(29)
	v_mov_b32_e32 v44, v136
	s_waitcnt vmcnt(28)
	v_mov_b32_e32 v45, v140
	v_mov_b32_e32 v132, v129
	v_mov_b32_e32 v140, v137
	v_pk_fma_f32 v[0:1], v[42:43], v[44:45], v[0:1]
	v_mov_b32_e32 v128, v130
	v_mov_b32_e32 v129, v134
	v_mov_b32_e32 v136, v138
	v_mov_b32_e32 v137, v142
	v_pk_fma_f32 v[0:1], v[132:133], v[140:141], v[0:1]
	v_mov_b32_e32 v134, v131
	v_mov_b32_e32 v142, v139
	v_pk_fma_f32 v[0:1], v[128:129], v[136:137], v[0:1]
	s_waitcnt vmcnt(27)
	v_mov_b32_e32 v130, v144
	s_waitcnt vmcnt(26)
	v_mov_b32_e32 v131, v148
	s_waitcnt vmcnt(25)
	v_mov_b32_e32 v138, v152
	s_waitcnt vmcnt(24)
	v_mov_b32_e32 v139, v156
	v_pk_fma_f32 v[0:1], v[134:135], v[142:143], v[0:1]
	v_mov_b32_e32 v148, v145
	v_mov_b32_e32 v156, v153
	v_pk_fma_f32 v[0:1], v[130:131], v[138:139], v[0:1]
	v_mov_b32_e32 v144, v146
	v_mov_b32_e32 v145, v150
	v_mov_b32_e32 v152, v154
	v_mov_b32_e32 v153, v158
	v_pk_fma_f32 v[0:1], v[148:149], v[156:157], v[0:1]
	v_mov_b32_e32 v150, v147
	v_mov_b32_e32 v158, v155
	v_pk_fma_f32 v[0:1], v[144:145], v[152:153], v[0:1]
	s_nop 0
	v_pk_fma_f32 v[0:1], v[150:151], v[158:159], v[0:1]
	v_lshl_add_u64 v[144:145], v[2:3], 0, s[4:5]
	v_lshl_add_u64 v[152:153], v[4:5], 0, s[4:5]
	v_lshl_add_u64 v[148:149], v[6:7], 0, s[4:5]
	v_lshl_add_u64 v[156:157], v[8:9], 0, s[4:5]
	global_load_dwordx4 v[128:131], v[144:145], off
	global_load_dwordx4 v[132:135], v[148:149], off
	global_load_dwordx4 v[136:139], v[152:153], off
	global_load_dwordx4 v[140:143], v[156:157], off
	s_nop 0
	global_load_dwordx4 v[144:147], v[144:145], off offset:16
	s_nop 0
	global_load_dwordx4 v[148:151], v[148:149], off offset:16
	s_nop 0
	global_load_dwordx4 v[152:155], v[152:153], off offset:16
	s_nop 0
	global_load_dwordx4 v[156:159], v[156:157], off offset:16
	s_add_u32 s4, s4, 32
	s_addc_u32 s5, s5, 0
	s_waitcnt vmcnt(31)
	v_mov_b32_e32 v42, v160
	s_waitcnt vmcnt(30)
	v_mov_b32_e32 v43, v164
	s_waitcnt vmcnt(29)
	v_mov_b32_e32 v44, v168
	s_waitcnt vmcnt(28)
	v_mov_b32_e32 v45, v172
	v_mov_b32_e32 v164, v161
	v_mov_b32_e32 v172, v169
	v_pk_fma_f32 v[0:1], v[42:43], v[44:45], v[0:1]
	v_mov_b32_e32 v160, v162
	v_mov_b32_e32 v161, v166
	v_mov_b32_e32 v168, v170
	v_mov_b32_e32 v169, v174
	v_pk_fma_f32 v[0:1], v[164:165], v[172:173], v[0:1]
	v_mov_b32_e32 v166, v163
	v_mov_b32_e32 v174, v171
	v_pk_fma_f32 v[0:1], v[160:161], v[168:169], v[0:1]
	s_waitcnt vmcnt(27)
	v_mov_b32_e32 v162, v176
	s_waitcnt vmcnt(26)
	v_mov_b32_e32 v163, v180
	s_waitcnt vmcnt(25)
	v_mov_b32_e32 v170, v184
	s_waitcnt vmcnt(24)
	v_mov_b32_e32 v171, v188
	v_pk_fma_f32 v[0:1], v[166:167], v[174:175], v[0:1]
	v_mov_b32_e32 v180, v177
	v_mov_b32_e32 v188, v185
	v_pk_fma_f32 v[0:1], v[162:163], v[170:171], v[0:1]
	v_mov_b32_e32 v176, v178
	v_mov_b32_e32 v177, v182
	v_mov_b32_e32 v184, v186
	v_mov_b32_e32 v185, v190
	v_pk_fma_f32 v[0:1], v[180:181], v[188:189], v[0:1]
	v_mov_b32_e32 v182, v179
	v_mov_b32_e32 v190, v187
	v_pk_fma_f32 v[0:1], v[176:177], v[184:185], v[0:1]
	s_nop 0
	v_pk_fma_f32 v[0:1], v[182:183], v[190:191], v[0:1]
	v_lshl_add_u64 v[176:177], v[2:3], 0, s[4:5]
	v_lshl_add_u64 v[184:185], v[4:5], 0, s[4:5]
	v_lshl_add_u64 v[180:181], v[6:7], 0, s[4:5]
	v_lshl_add_u64 v[188:189], v[8:9], 0, s[4:5]
	global_load_dwordx4 v[160:163], v[176:177], off
	global_load_dwordx4 v[164:167], v[180:181], off
	global_load_dwordx4 v[168:171], v[184:185], off
	global_load_dwordx4 v[172:175], v[188:189], off
	s_nop 0
	global_load_dwordx4 v[176:179], v[176:177], off offset:16
	s_nop 0
	global_load_dwordx4 v[180:183], v[180:181], off offset:16
	s_nop 0
	global_load_dwordx4 v[184:187], v[184:185], off offset:16
	s_nop 0
	global_load_dwordx4 v[188:191], v[188:189], off offset:16
	s_add_u32 s4, s4, 32
	s_addc_u32 s5, s5, 0
	s_waitcnt vmcnt(31)
	v_mov_b32_e32 v42, v64
	s_waitcnt vmcnt(30)
	v_mov_b32_e32 v43, v68
	s_waitcnt vmcnt(29)
	v_mov_b32_e32 v44, v72
	s_waitcnt vmcnt(28)
	v_mov_b32_e32 v45, v76
	v_mov_b32_e32 v68, v65
	v_mov_b32_e32 v76, v73
	v_pk_fma_f32 v[0:1], v[42:43], v[44:45], v[0:1]
	v_mov_b32_e32 v64, v66
	v_mov_b32_e32 v65, v70
	v_mov_b32_e32 v72, v74
	v_mov_b32_e32 v73, v78
	v_pk_fma_f32 v[0:1], v[68:69], v[76:77], v[0:1]
	v_mov_b32_e32 v70, v67
	v_mov_b32_e32 v78, v75
	v_pk_fma_f32 v[0:1], v[64:65], v[72:73], v[0:1]
	s_waitcnt vmcnt(27)
	v_mov_b32_e32 v66, v80
	s_waitcnt vmcnt(26)
	v_mov_b32_e32 v67, v84
	s_waitcnt vmcnt(25)
	v_mov_b32_e32 v74, v88
	s_waitcnt vmcnt(24)
	v_mov_b32_e32 v75, v92
	v_pk_fma_f32 v[0:1], v[70:71], v[78:79], v[0:1]
	v_mov_b32_e32 v84, v81
	v_mov_b32_e32 v92, v89
	v_pk_fma_f32 v[0:1], v[66:67], v[74:75], v[0:1]
	v_mov_b32_e32 v80, v82
	v_mov_b32_e32 v81, v86
	v_mov_b32_e32 v88, v90
	v_mov_b32_e32 v89, v94
	v_pk_fma_f32 v[0:1], v[84:85], v[92:93], v[0:1]
	v_mov_b32_e32 v86, v83
	v_mov_b32_e32 v94, v91
	v_pk_fma_f32 v[0:1], v[80:81], v[88:89], v[0:1]
	s_nop 0
	v_pk_fma_f32 v[0:1], v[86:87], v[94:95], v[0:1]
	s_waitcnt vmcnt(23)
	v_mov_b32_e32 v42, v96
	s_waitcnt vmcnt(22)
	v_mov_b32_e32 v43, v100
	s_waitcnt vmcnt(21)
	v_mov_b32_e32 v44, v104
	s_waitcnt vmcnt(20)
	v_mov_b32_e32 v45, v108
	v_mov_b32_e32 v100, v97
	v_mov_b32_e32 v108, v105
	v_pk_fma_f32 v[0:1], v[42:43], v[44:45], v[0:1]
	v_mov_b32_e32 v96, v98
	v_mov_b32_e32 v97, v102
	v_mov_b32_e32 v104, v106
	v_mov_b32_e32 v105, v110
	v_pk_fma_f32 v[0:1], v[100:101], v[108:109], v[0:1]
	v_mov_b32_e32 v102, v99
	v_mov_b32_e32 v110, v107
	v_pk_fma_f32 v[0:1], v[96:97], v[104:105], v[0:1]
	s_waitcnt vmcnt(19)
	v_mov_b32_e32 v98, v112
	s_waitcnt vmcnt(18)
	v_mov_b32_e32 v99, v116
	s_waitcnt vmcnt(17)
	v_mov_b32_e32 v106, v120
	s_waitcnt vmcnt(16)
	v_mov_b32_e32 v107, v124
	v_pk_fma_f32 v[0:1], v[102:103], v[110:111], v[0:1]
	v_mov_b32_e32 v116, v113
	v_mov_b32_e32 v124, v121
	v_pk_fma_f32 v[0:1], v[98:99], v[106:107], v[0:1]
	v_mov_b32_e32 v112, v114
	v_mov_b32_e32 v113, v118
	v_mov_b32_e32 v120, v122
	v_mov_b32_e32 v121, v126
	v_pk_fma_f32 v[0:1], v[116:117], v[124:125], v[0:1]
	v_mov_b32_e32 v118, v115
	v_mov_b32_e32 v126, v123
	v_pk_fma_f32 v[0:1], v[112:113], v[120:121], v[0:1]
	s_nop 0
	v_pk_fma_f32 v[0:1], v[118:119], v[126:127], v[0:1]
	s_waitcnt vmcnt(15)
	v_mov_b32_e32 v42, v128
	s_waitcnt vmcnt(14)
	v_mov_b32_e32 v43, v132
	s_waitcnt vmcnt(13)
	v_mov_b32_e32 v44, v136
	s_waitcnt vmcnt(12)
	v_mov_b32_e32 v45, v140
	v_mov_b32_e32 v132, v129
	v_mov_b32_e32 v140, v137
	v_pk_fma_f32 v[0:1], v[42:43], v[44:45], v[0:1]
	v_mov_b32_e32 v128, v130
	v_mov_b32_e32 v129, v134
	v_mov_b32_e32 v136, v138
	v_mov_b32_e32 v137, v142
	v_pk_fma_f32 v[0:1], v[132:133], v[140:141], v[0:1]
	v_mov_b32_e32 v134, v131
	v_mov_b32_e32 v142, v139
	v_pk_fma_f32 v[0:1], v[128:129], v[136:137], v[0:1]
	s_waitcnt vmcnt(11)
	v_mov_b32_e32 v130, v144
	s_waitcnt vmcnt(10)
	v_mov_b32_e32 v131, v148
	s_waitcnt vmcnt(9)
	v_mov_b32_e32 v138, v152
	s_waitcnt vmcnt(8)
	v_mov_b32_e32 v139, v156
	v_pk_fma_f32 v[0:1], v[134:135], v[142:143], v[0:1]
	v_mov_b32_e32 v148, v145
	v_mov_b32_e32 v156, v153
	v_pk_fma_f32 v[0:1], v[130:131], v[138:139], v[0:1]
	v_mov_b32_e32 v144, v146
	v_mov_b32_e32 v145, v150
	v_mov_b32_e32 v152, v154
	v_mov_b32_e32 v153, v158
	v_pk_fma_f32 v[0:1], v[148:149], v[156:157], v[0:1]
	v_mov_b32_e32 v150, v147
	v_mov_b32_e32 v158, v155
	v_pk_fma_f32 v[0:1], v[144:145], v[152:153], v[0:1]
	s_nop 0
	v_pk_fma_f32 v[0:1], v[150:151], v[158:159], v[0:1]
	s_waitcnt vmcnt(7)
	v_mov_b32_e32 v42, v160
	s_waitcnt vmcnt(6)
	v_mov_b32_e32 v43, v164
	s_waitcnt vmcnt(5)
	v_mov_b32_e32 v44, v168
	s_waitcnt vmcnt(4)
	v_mov_b32_e32 v45, v172
	v_mov_b32_e32 v164, v161
	v_mov_b32_e32 v172, v169
	v_pk_fma_f32 v[0:1], v[42:43], v[44:45], v[0:1]
	v_mov_b32_e32 v160, v162
	v_mov_b32_e32 v161, v166
	v_mov_b32_e32 v168, v170
	v_mov_b32_e32 v169, v174
	v_pk_fma_f32 v[0:1], v[164:165], v[172:173], v[0:1]
	v_mov_b32_e32 v166, v163
	v_mov_b32_e32 v174, v171
	v_pk_fma_f32 v[0:1], v[160:161], v[168:169], v[0:1]
	s_waitcnt vmcnt(3)
	v_mov_b32_e32 v162, v176
	s_waitcnt vmcnt(2)
	v_mov_b32_e32 v163, v180
	s_waitcnt vmcnt(1)
	v_mov_b32_e32 v170, v184
	s_waitcnt vmcnt(0)
	v_mov_b32_e32 v171, v188
	v_pk_fma_f32 v[0:1], v[166:167], v[174:175], v[0:1]
	v_mov_b32_e32 v180, v177
	v_mov_b32_e32 v188, v185
	v_pk_fma_f32 v[0:1], v[162:163], v[170:171], v[0:1]
	v_mov_b32_e32 v176, v178
	v_mov_b32_e32 v177, v182
	v_mov_b32_e32 v184, v186
	v_mov_b32_e32 v185, v190
	v_pk_fma_f32 v[0:1], v[180:181], v[188:189], v[0:1]
	v_mov_b32_e32 v182, v179
	v_mov_b32_e32 v190, v187
	v_pk_fma_f32 v[0:1], v[176:177], v[184:185], v[0:1]
	s_nop 0
	v_pk_fma_f32 v[0:1], v[182:183], v[190:191], v[0:1]
	v_cvt_f32_u32_e32 v2, v216
	s_mov_b32 s4, 0x3fb8aa3b
	s_mov_b32 s5, 0xc2ce8ed0
	s_mov_b32 s8, 0x42b17218
	v_mul_f32_e32 v2, 0xbe99999a, v2
	v_mul_f32_e32 v3, 0x3fb8aa3b, v2
	v_fma_f32 v4, v2, s4, -v3
	v_rndne_f32_e32 v5, v3
	v_fmac_f32_e32 v4, 0x32a5705f, v2
	v_sub_f32_e32 v3, v3, v5
	v_add_f32_e32 v3, v3, v4
	v_cvt_i32_f32_e32 v4, v5
	v_mul_f32_e32 v5, 0x3fb8aa3b, v0
	v_rndne_f32_e32 v6, v5
	v_exp_f32_e32 v3, v3
	v_sub_f32_e32 v7, v5, v6
	v_fma_f32 v5, v0, s4, -v5
	v_fmac_f32_e32 v5, 0x32a5705f, v0
	v_add_f32_e32 v5, v7, v5
	v_exp_f32_e32 v5, v5
	v_cvt_i32_f32_e32 v6, v6
	v_ldexp_f32 v3, v3, v4
	v_cmp_ngt_f32_e32 vcc, s5, v2
	v_mov_b32_e32 v4, 0x7f800000
	s_nop 0
	v_cndmask_b32_e32 v3, 0, v3, vcc
	v_cmp_nlt_f32_e32 vcc, s8, v2
	s_nop 1
	v_cndmask_b32_e32 v2, v4, v3, vcc
	v_mov_b32_e32 v3, 0x3f4ccccd
	v_fmac_f32_e32 v3, 0xbf19999a, v2
	v_ldexp_f32 v2, v5, v6
	v_mul_f32_e32 v5, 0x3fb8aa3b, v1
	v_rndne_f32_e32 v6, v5
	v_sub_f32_e32 v7, v5, v6
	v_fma_f32 v5, v1, s4, -v5
	v_fmac_f32_e32 v5, 0x32a5705f, v1
	v_add_f32_e32 v5, v7, v5
	v_exp_f32_e32 v5, v5
	v_cvt_i32_f32_e32 v6, v6
	v_cmp_ngt_f32_e32 vcc, s5, v0
	s_nop 1
	v_cndmask_b32_e32 v2, 0, v2, vcc
	v_cmp_nlt_f32_e32 vcc, s8, v0
	s_nop 1
	v_cndmask_b32_e32 v0, v4, v2, vcc
	v_ldexp_f32 v2, v5, v6
	v_cmp_ngt_f32_e32 vcc, s5, v1
	v_readlane_b32 s4, v252, 50
	v_readlane_b32 s5, v252, 51
	v_cndmask_b32_e32 v2, 0, v2, vcc
	v_cmp_nlt_f32_e32 vcc, s8, v1
	s_nop 1
	v_cndmask_b32_e32 v1, v4, v2, vcc
	v_sub_f32_e32 v0, v0, v1
	v_add_f32_e32 v0, v3, v0
	v_lshlrev_b32_e32 v2, 3, v216
	v_sub_f32_e32 v1, 1.0, v3
	global_store_dwordx2 v2, v[0:1], s[4:5]

.LBB0_298:
	v_cvt_pk_bf16_f32 v146, v122, s0
	v_cvt_pk_bf16_f32 v147, v123, s0
	v_pk_mul_f32 v[132:133], v[102:103], v[122:123]
	v_pk_mul_f32 v[122:123], v[114:115], v[122:123]
	s_add_i32 s1, s0, 8
	v_add_f32_e32 v122, v122, v123
	s_cmpk_lt_u32 s0, 0xf8
	v_sub_f32_e32 v132, v132, v133
	v_add_f32_e32 v122, v121, v122
	s_cselect_b64 s[8:9], -1, 0
	v_add_f32_e32 v120, v120, v132
	v_cvt_pk_bf16_f32 v149, v122, s0
	v_pk_mul_f32 v[122:123], v[114:115], v[122:123] op_sel_hi:[1,0]
	s_and_b64 vcc, s[8:9], exec
	v_cvt_pk_bf16_f32 v148, v120, s0
	v_pk_fma_f32 v[132:133], v[102:103], v[120:121], v[122:123] neg_lo:[0,0,1] neg_hi:[0,0,1]
	v_pk_fma_f32 v[120:121], v[102:103], v[120:121], v[122:123] op_sel_hi:[1,0,1]
	s_cselect_b32 s8, s1, s0
	v_mov_b32_e32 v133, v121
	s_mov_b32 s0, s1
	v_lshl_add_u32 v144, s8, 9, v101
	v_pk_add_f32 v[118:119], v[118:119], v[132:133]
	ds_read2st64_b32 v[120:121], v144 offset1:1
	ds_read2st64_b32 v[122:123], v144 offset0:2 offset1:3
	ds_read2st64_b32 v[134:135], v144 offset0:4 offset1:5
	ds_read2st64_b32 v[136:137], v144 offset0:6 offset1:7
	ds_read2st64_b32 v[138:139], v144 offset0:8 offset1:9
	ds_read2st64_b32 v[140:141], v144 offset0:10 offset1:11
	ds_read2st64_b32 v[142:143], v144 offset0:12 offset1:13
	ds_read2st64_b32 v[144:145], v144 offset0:14 offset1:15
	ds_write_b16 v131, v146
	ds_write_b16 v131, v147 offset:128
	ds_write_b16 v131, v148 offset:512
	ds_write_b16 v131, v149 offset:640
	v_cvt_pk_bf16_f32 v146, v118, s0
	v_cvt_pk_bf16_f32 v147, v119, s0
	v_pk_mul_f32 v[132:133], v[102:103], v[118:119]
	v_pk_mul_f32 v[118:119], v[102:103], v[118:119] op_sel:[0,1] op_sel_hi:[1,0]
	v_sub_f32_e32 v132, v132, v133
	v_add_f32_e32 v118, v118, v119
	v_add_f32_e32 v110, v110, v132
	v_add_f32_e32 v118, v111, v118
	v_cvt_pk_bf16_f32 v111, v110, s0
	v_cvt_pk_bf16_f32 v132, v118, s0
	v_pk_mul_f32 v[118:119], v[102:103], v[118:119] op_sel_hi:[1,0]
	ds_write_b16 v131, v146 offset:1024
	ds_write_b16 v131, v147 offset:1152
	ds_write_b16 v131, v111 offset:1536
	ds_write_b16 v131, v132 offset:1664
	v_pk_fma_f32 v[132:133], v[114:115], v[110:111], v[118:119]
	v_pk_fma_f32 v[146:147], v[114:115], v[110:111], v[118:119] op_sel_hi:[1,0,1] neg_lo:[0,0,1] neg_hi:[0,0,1]
	s_waitcnt lgkmcnt(14)
	v_mov_b32_e32 v118, v122
	v_mov_b32_e32 v133, v147
	v_mov_b32_e32 v119, v123
	v_pk_add_f32 v[122:123], v[116:117], v[132:133]
	s_waitcnt lgkmcnt(13)
	v_mov_b32_e32 v111, v135
	v_mov_b32_e32 v110, v134
	v_cvt_pk_bf16_f32 v134, v123, s0
	v_cvt_pk_bf16_f32 v135, v122, s0
	v_pk_mul_f32 v[132:133], v[102:103], v[122:123] op_sel:[0,1] op_sel_hi:[1,0]
	v_pk_mul_f32 v[122:123], v[102:103], v[122:123]
	v_sub_f32_e32 v132, v132, v133
	v_add_f32_e32 v123, v122, v123
	v_add_f32_e32 v122, v104, v132
	v_add_f32_e32 v132, v105, v123
	ds_write_b16 v131, v134 offset:2048
	ds_write_b16 v131, v135 offset:2176
	v_cvt_pk_bf16_f32 v123, v122, s0
	v_cvt_pk_bf16_f32 v134, v132, s0
	v_pk_mul_f32 v[132:133], v[102:103], v[132:133] op_sel_hi:[1,0]
	ds_write_b16 v131, v123 offset:2560
	ds_write_b16 v131, v134 offset:2688
	v_pk_fma_f32 v[134:135], v[114:115], v[122:123], v[132:133]
	v_pk_fma_f32 v[122:123], v[114:115], v[122:123], v[132:133] op_sel_hi:[1,0,1] neg_lo:[0,0,1] neg_hi:[0,0,1]
	s_waitcnt lgkmcnt(14)
	v_mov_b32_e32 v116, v137
	v_mov_b32_e32 v135, v123
	v_pk_add_f32 v[122:123], v[112:113], v[134:135]
	v_mov_b32_e32 v117, v136
	v_pk_mul_f32 v[132:133], v[102:103], v[122:123] op_sel:[0,1] op_sel_hi:[1,0]
	v_cvt_pk_bf16_f32 v134, v123, s0
	v_cvt_pk_bf16_f32 v135, v122, s0
	v_pk_mul_f32 v[122:123], v[102:103], v[122:123]
	v_sub_f32_e32 v132, v132, v133
	v_add_f32_e32 v123, v122, v123
	v_add_f32_e32 v122, v106, v132
	v_add_f32_e32 v132, v107, v123
	v_cvt_pk_bf16_f32 v123, v122, s0
	ds_write_b16 v131, v134 offset:3072
	ds_write_b16 v131, v135 offset:3200
	v_cvt_pk_bf16_f32 v134, v132, s0
	v_pk_mul_f32 v[132:133], v[114:115], v[132:133] op_sel_hi:[1,0]
	ds_write_b16 v131, v123 offset:3584
	ds_write_b16 v131, v134 offset:3712
	v_pk_fma_f32 v[134:135], v[102:103], v[122:123], v[132:133] neg_lo:[0,0,1] neg_hi:[0,0,1]
	v_pk_fma_f32 v[122:123], v[102:103], v[122:123], v[132:133] op_sel_hi:[1,0,1]
	v_mov_b32_e32 v105, v139
	v_mov_b32_e32 v135, v123
	v_mov_b32_e32 v104, v138
	v_mov_b32_e32 v112, v141
	v_mov_b32_e32 v113, v140
	s_waitcnt lgkmcnt(14)
	v_mov_b32_e32 v107, v143
	v_mov_b32_e32 v106, v142
	v_add_u32_e32 v131, 0x1000, v131
	v_pk_add_f32 v[122:123], v[108:109], v[134:135]
	v_mov_b32_e32 v108, v144
	v_mov_b32_e32 v109, v145
	s_cbranch_vccnz .LBB0_298
